# baseline (speedup 1.0000x reference)
; __device__ __forceinline__ void xcd_barrier(const XcdBarrier& b) {
;     asm volatile("s_waitcnt vmcnt(0)" ::: "memory");
;     __syncthreads();
;     if (threadIdx.x == 0) {
;         unsigned* bar = b.bar;
;         __builtin_amdgcn_s_waitcnt(0);
;         unsigned nloc = b.st[0], nx = b.st[1];
;         if (nloc == 0u) { xcd_barrier_complete(bar, b.x, nloc, nx); b.st[0] = nloc; b.st[1] = nx; }
; __global__ void __launch_bounds__(512) fwd_megakernel(Args args) {
;     ...
;                 for (int i = 0;; ++i) {
;                     const int U = i * G + vcu; if (U >= nun) break;
;                     int sh, qb, sb, S_;
;                     if (pass == 0) { sh = U >> 5; qb = U & 31; S_ = S_S; sb = NPROMPT + (sh >> 4) * S_S; } else { sh = U >> 3; qb = U & 7; S_ = S_P; sb = (sh >> 4) * S_P; }
;                     const int head = sh & 15, tok = sb + qb * 512 + 64 * wave + r;
;                     bf16_t* qrow_a = Q1 + (size_t)tok * 1536 + head * 96; bf16_t* qrow_b = qrow_a + (size_t)32 * 1536;
.Lp11_drain:
	v_exp_f32_e32 v64, v64
	v_exp_f32_e32 v65, v65
	v_exp_f32_e32 v66, v66
	v_exp_f32_e32 v67, v67
	v_exp_f32_e32 v68, v68
	v_exp_f32_e32 v69, v69
	v_cvt_pk_bf16_f32 v230, v64, v65
	v_cvt_pk_bf16_f32 v231, v66, v67
	v_exp_f32_e32 v70, v70
	v_exp_f32_e32 v71, v71
	v_exp_f32_e32 v72, v72
	v_cvt_pk_bf16_f32 v232, v68, v69
	v_exp_f32_e32 v73, v73
	v_exp_f32_e32 v74, v74
	v_cvt_pk_bf16_f32 v233, v70, v71
	v_exp_f32_e32 v75, v75
	v_exp_f32_e32 v76, v76
	v_exp_f32_e32 v77, v77
	v_cvt_pk_bf16_f32 v234, v72, v73
	v_cvt_pk_bf16_f32 v235, v74, v75
	v_exp_f32_e32 v78, v78
	v_exp_f32_e32 v79, v79
	v_cvt_pk_bf16_f32 v236, v76, v77
	v_cvt_pk_bf16_f32 v237, v78, v79
	v_add_f32_e32 v172, v172, v64
	v_add_f32_e32 v173, v173, v65
	v_add_f32_e32 v172, v172, v66
	v_add_f32_e32 v173, v173, v67
	v_add_f32_e32 v172, v172, v68
	v_add_f32_e32 v173, v173, v69
	v_add_f32_e32 v172, v172, v70
	v_add_f32_e32 v173, v173, v71
	v_add_f32_e32 v172, v172, v72
	v_add_f32_e32 v173, v173, v73
	v_add_f32_e32 v172, v172, v74
	v_add_f32_e32 v173, v173, v75
	v_add_f32_e32 v172, v172, v76
	v_add_f32_e32 v173, v173, v77
	v_add_f32_e32 v172, v172, v78
	v_add_f32_e32 v173, v173, v79
	s_nop 1
	v_mfma_f32_32x32x16_bf16 v[16:31], v[248:251], v[230:233], v[16:31]
	v_mfma_f32_32x32x16_bf16 v[0:15], v[252:255], v[230:233], v[0:15]
	v_mfma_f32_32x32x16_bf16 v[16:31], v[214:217], v[234:237], v[16:31]
	v_mfma_f32_32x32x16_bf16 v[0:15], v[218:221], v[234:237], v[0:15]
	s_waitcnt vmcnt(0)
	s_waitcnt lgkmcnt(0)
	s_barrier
	s_add_i32 s20, s38, 1
	s_mul_i32 s20, s20, s88
	s_add_i32 s20, s20, s80
	s_cmp_ge_i32 s20, s37
	s_cbranch_scc1 .Lp11_nopf
	s_lshl_b32 s21, s20, 5
	s_cmp_eq_u64 s[16:17], 0
	s_cbranch_scc1 .Lp11_pf_samp
	s_ashr_i32 s22, s20, 3
	s_and_b32 s23, s20, 7
	s_and_b32 s24, s21, 0xfffff000
	s_branch .Lp11_pf_go
.Lp11_pf_samp:
	s_ashr_i32 s22, s20, 5
	s_and_b32 s23, s20, 31
	s_and_b32 s24, s21, 0xffffc000
	s_add_i32 s24, s24, 0x4000
.Lp11_pf_go:
	s_lshl_b32 s23, s23, 9
	s_add_i32 s23, s23, s24
	s_and_b32 s22, s22, 15
	s_mul_i32 s22, s22, 0xc0
	v_add_u32_e32 v96, s23, v208
	v_mov_b64_e32 v[98:99], s[68:69]
	v_mad_i64_i32 v[98:99], s[24:25], v96, s28, v[98:99]
	s_mov_b32 s23, 0
	v_lshl_add_u64 v[98:99], v[98:99], 0, s[22:23]
	global_load_dword v213, v[98:99], off
	global_load_dword v213, v[98:99], off offset:128
	v_lshl_add_u64 v[98:99], v[98:99], 0, s[6:7]
	global_load_dword v213, v[98:99], off
	global_load_dword v213, v[98:99], off offset:128
.Lp11_nopf:
	s_branch .LBB0_1115
.LBB0_1136:
	s_waitcnt vmcnt(0)
	s_barrier
	s_mov_b64 s[0:1], exec
	v_readlane_b32 s4, v247, 2
	v_readlane_b32 s12, v247, 39
	v_readlane_b32 s5, v247, 3
	v_readlane_b32 s26, v247, 53
	v_readlane_b32 s27, v247, 54
	v_readlane_b32 s70, v247, 57
	s_and_b64 s[4:5], s[0:1], s[4:5]
	s_mov_b64 s[66:67], s[26:27]
	v_readlane_b32 s65, v247, 38
	v_readlane_b32 s71, v247, 58
	v_readlane_b32 s13, v247, 40
	v_readlane_b32 s14, v247, 41
	v_readlane_b32 s15, v247, 42
	v_readlane_b32 s16, v247, 43
	v_readlane_b32 s17, v247, 44
	v_readlane_b32 s18, v247, 45
	v_readlane_b32 s19, v247, 46
	v_readlane_b32 s20, v247, 47
	v_readlane_b32 s21, v247, 48
	v_readlane_b32 s22, v247, 49
	v_readlane_b32 s23, v247, 50
	v_readlane_b32 s24, v247, 51
	v_readlane_b32 s25, v247, 52
	s_mov_b64 exec, s[4:5]
	s_cbranch_execz .LBB0_1188
	s_add_i32 s4, 0, 0x23fe0
	v_mov_b32_e32 v0, s4
	s_waitcnt vmcnt(0) expcnt(0) lgkmcnt(0)
	ds_read_b32 v2, v0
	s_add_i32 s4, 0, 0x23fe4
	v_mov_b32_e32 v0, s4
	ds_read_b32 v0, v0
	s_waitcnt lgkmcnt(1)
	v_cmp_ne_u32_e32 vcc, 0, v2
	s_cbranch_vccnz .LBB0_1152
	v_readlane_b32 s4, v247, 0
	s_mul_i32 s20, s89, s4
	s_add_u32 s4, s90, 0x1000
	s_addc_u32 s5, s91, 0
	s_add_u32 s6, s90, 0x1100
	s_addc_u32 s7, s91, 0
	s_add_u32 s8, s90, 0x1200
	s_addc_u32 s9, s91, 0
	s_add_u32 s12, s90, 0x1300
	s_mul_i32 s20, s20, s88
	s_addc_u32 s13, s91, 0
	s_mov_b32 s21, 1
	v_mov_b32_e32 v16, 0
	s_branch .LBB0_1140
